# retention out-projection GEMM epilogue: gate loads of a row issued together, no per-fragment store wait
# baseline (speedup 1.0000x reference)
.LBB0_859:
	v_lshl_add_u32 v182, s0, 8, v129
	v_mul_hi_i32 v143, v182, s38
	v_lshrrev_b32_e32 v178, 31, v143
	v_ashrrev_i32_e32 v143, 11, v143
	v_add_u32_e32 v187, v143, v178
	v_mad_i32_i24 v143, v187, s39, v182
	v_lshl_or_b32 v142, s1, 8, v153
	v_lshl_add_u32 v178, v187, 13, v177
	v_lshlrev_b32_e32 v179, 8, v187
	v_cmp_gt_i32_e64 s[0:1], s85, v143
	v_readlane_b32 s56, v254, 59
	v_readlane_b32 s57, v254, 60
	v_cndmask_b32_e64 v178, v178, v179, s[0:1]
	v_add_u32_e32 v178, v178, v143
	v_readlane_b32 s60, v254, 63
	v_readlane_b32 s61, v255, 0
	v_mov_b32_e32 v183, s57
	v_mov_b32_e32 v185, s56
	v_mov_b32_e32 v184, s61
	v_mov_b32_e32 v186, s60
	v_ashrrev_i32_e32 v179, 31, v178
	v_cndmask_b32_e64 v181, v183, v184, s[0:1]
	v_cndmask_b32_e64 v180, v185, v186, s[0:1]
	v_lshlrev_b64 v[192:193], 12, v[178:179]
	v_lshl_add_u64 v[178:179], v[180:181], 0, v[192:193]
	v_cndmask_b32_e64 v180, v187, 4, s[0:1]
	v_ashrrev_i32_e32 v143, 31, v142
	v_mul_hi_i32_i24_e32 v181, 0x6000, v180
	v_mul_i32_i24_e32 v180, 0x6000, v180
	v_lshlrev_b64 v[142:143], 2, v[142:143]
	v_lshl_add_u64 v[180:181], s[12:13], 0, v[180:181]
	v_lshl_add_u64 v[230:231], v[180:181], 0, v[142:143]
	global_load_dwordx4 v[188:191], v[230:231], off
	global_load_dwordx4 v[234:237], v[230:231], off offset:64
	global_load_dwordx4 v[238:241], v[230:231], off offset:512
	global_load_dwordx4 v[242:245], v[230:231], off offset:576
	v_lshl_add_u64 v[210:211], v[178:179], 0, v[142:143]
	global_load_dwordx4 v[198:201], v[210:211], off
	v_or_b32_e32 v187, 16, v182
	v_mul_hi_i32 v197, v187, s38
	v_lshrrev_b32_e32 v202, 31, v197
	v_ashrrev_i32_e32 v197, 11, v197
	v_add_u32_e32 v197, v197, v202
	v_mad_i32_i24 v187, v197, s39, v187
	v_readlane_b32 s58, v254, 61
	v_readlane_b32 s59, v254, 62
	v_readlane_b32 s62, v255, 1
	v_readlane_b32 s63, v255, 2
	v_readlane_b32 s70, v255, 9
	v_readlane_b32 s71, v255, 10
	v_lshl_add_u32 v202, v197, 13, v177
	v_lshlrev_b32_e32 v203, 8, v197
	v_cmp_gt_i32_e32 vcc, s85, v187
	s_mov_b64 s[62:63], s[50:51]
	v_readlane_b32 s70, v255, 21
	v_cndmask_b32_e32 v204, v202, v203, vcc
	s_mov_b64 s[60:61], s[48:49]
	v_readlane_b32 s71, v255, 22
	v_add_u32_e32 v204, v204, v187
	v_mov_b32_e32 v178, s61
	v_mov_b32_e32 v179, s71
	v_mov_b32_e32 v180, s60
	v_mov_b32_e32 v181, s70
	v_ashrrev_i32_e32 v205, 31, v204
	v_cndmask_b32_e64 v203, v178, v179, s[0:1]
	v_cndmask_b32_e64 v202, v180, v181, s[0:1]
	v_cndmask_b32_e32 v207, v183, v184, vcc
	v_cndmask_b32_e32 v206, v185, v186, vcc
	v_lshlrev_b64 v[232:233], 12, v[204:205]
	v_lshl_add_u64 v[192:193], v[202:203], 0, v[192:193]
	v_lshl_add_u64 v[214:215], v[206:207], 0, v[232:233]
	v_lshl_add_u64 v[192:193], v[192:193], 0, v[142:143]
	v_lshl_add_u64 v[226:227], v[214:215], 0, v[142:143]
	global_load_dwordx4 v[202:205], v[210:211], off offset:64
	global_load_dwordx4 v[206:209], v[210:211], off offset:512
	s_nop 0
	global_load_dwordx4 v[210:213], v[210:211], off offset:576
	s_nop 0
	global_load_dwordx4 v[214:217], v[226:227], off
	global_load_dwordx4 v[218:221], v[226:227], off offset:64
	global_load_dwordx4 v[222:225], v[226:227], off offset:512
	s_nop 0
	global_load_dwordx4 v[226:229], v[226:227], off offset:576
	s_mov_b64 s[0:1], -1
	v_readlane_b32 s64, v255, 3
	v_readlane_b32 s65, v255, 4
	v_readlane_b32 s66, v255, 5
	v_readlane_b32 s67, v255, 6
	v_readlane_b32 s68, v255, 7
	v_readlane_b32 s69, v255, 8
	s_mov_b64 s[58:59], s[46:47]
	s_mov_b64 s[56:57], s[44:45]
	s_waitcnt vmcnt(0)
	v_pk_mul_f32 v[126:127], v[126:127], v[190:191]
	v_pk_mul_f32 v[124:125], v[124:125], v[188:189]
	v_pk_fma_f32 v[126:127], v[200:201], s[18:19], v[126:127] op_sel_hi:[1,0,1]
	v_pk_fma_f32 v[124:125], v[198:199], s[18:19], v[124:125] op_sel_hi:[1,0,1]
	global_store_dwordx4 v[192:193], v[124:127], off
	v_pk_mul_f32 v[122:123], v[122:123], v[236:237]
	v_pk_mul_f32 v[120:121], v[120:121], v[234:235]
	v_pk_fma_f32 v[122:123], v[204:205], s[18:19], v[122:123] op_sel_hi:[1,0,1]
	v_pk_fma_f32 v[120:121], v[202:203], s[18:19], v[120:121] op_sel_hi:[1,0,1]
	global_store_dwordx4 v[192:193], v[120:123], off offset:64
	v_pk_mul_f32 v[118:119], v[118:119], v[240:241]
	v_pk_mul_f32 v[116:117], v[116:117], v[238:239]
	v_pk_fma_f32 v[118:119], v[208:209], s[18:19], v[118:119] op_sel_hi:[1,0,1]
	v_pk_fma_f32 v[116:117], v[206:207], s[18:19], v[116:117] op_sel_hi:[1,0,1]
	global_store_dwordx4 v[192:193], v[116:119], off offset:512
	v_cndmask_b32_e64 v120, v197, 4, vcc
	v_mul_hi_i32_i24_e32 v121, 0x6000, v120
	v_mul_i32_i24_e32 v120, 0x6000, v120
	v_lshl_add_u64 v[120:121], s[12:13], 0, v[120:121]
	v_lshl_add_u64 v[198:199], v[120:121], 0, v[142:143]
	v_cndmask_b32_e32 v121, v178, v179, vcc
	v_cndmask_b32_e32 v120, v180, v181, vcc
	v_pk_mul_f32 v[114:115], v[114:115], v[244:245]
	v_pk_mul_f32 v[112:113], v[112:113], v[242:243]
	v_pk_fma_f32 v[114:115], v[212:213], s[18:19], v[114:115] op_sel_hi:[1,0,1]
	v_pk_fma_f32 v[112:113], v[210:211], s[18:19], v[112:113] op_sel_hi:[1,0,1]
	global_store_dwordx4 v[192:193], v[112:115], off offset:576
	global_load_dwordx4 v[112:115], v[198:199], off
	v_or_b32_e32 v116, 32, v182
	v_mul_hi_i32 v117, v116, s38
	v_lshrrev_b32_e32 v118, 31, v117
	v_ashrrev_i32_e32 v117, 11, v117
	v_add_u32_e32 v187, v117, v118
	v_mad_i32_i24 v116, v187, s39, v116
	v_lshl_add_u32 v117, v187, 13, v177
	v_lshlrev_b32_e32 v118, 8, v187
	v_cmp_gt_i32_e64 s[10:11], s85, v116
	s_waitcnt vmcnt(0)
	v_pk_mul_f32 v[110:111], v[110:111], v[114:115]
	v_cndmask_b32_e64 v117, v117, v118, s[10:11]
	v_add_u32_e32 v116, v117, v116
	v_ashrrev_i32_e32 v117, 31, v116
	v_cndmask_b32_e64 v119, v183, v184, s[10:11]
	v_cndmask_b32_e64 v118, v185, v186, s[10:11]
	v_lshlrev_b64 v[192:193], 12, v[116:117]
	v_lshl_add_u64 v[116:117], v[118:119], 0, v[192:193]
	v_lshl_add_u64 v[118:119], v[120:121], 0, v[232:233]
	v_pk_mul_f32 v[108:109], v[108:109], v[112:113]
	v_lshl_add_u64 v[188:189], v[116:117], 0, v[142:143]
	v_lshl_add_u64 v[200:201], v[118:119], 0, v[142:143]
	v_pk_fma_f32 v[110:111], v[216:217], s[18:19], v[110:111] op_sel_hi:[1,0,1]
	v_pk_fma_f32 v[108:109], v[214:215], s[18:19], v[108:109] op_sel_hi:[1,0,1]
	global_load_dwordx4 v[116:119], v[188:189], off
	global_load_dwordx4 v[120:123], v[188:189], off offset:64
	global_load_dwordx4 v[124:127], v[188:189], off offset:512
	s_nop 0
	global_load_dwordx4 v[188:191], v[188:189], off offset:576
	s_nop 0
	global_store_dwordx4 v[200:201], v[108:111], off
	global_load_dwordx4 v[108:111], v[198:199], off offset:64
	s_waitcnt vmcnt(0)
	v_pk_mul_f32 v[106:107], v[106:107], v[110:111]
	v_pk_mul_f32 v[104:105], v[104:105], v[108:109]
	v_pk_fma_f32 v[106:107], v[220:221], s[18:19], v[106:107] op_sel_hi:[1,0,1]
	v_pk_fma_f32 v[104:105], v[218:219], s[18:19], v[104:105] op_sel_hi:[1,0,1]
	global_store_dwordx4 v[200:201], v[104:107], off offset:64
	global_load_dwordx4 v[104:107], v[198:199], off offset:512
	s_waitcnt vmcnt(0)
	v_pk_mul_f32 v[102:103], v[102:103], v[106:107]
	v_pk_mul_f32 v[100:101], v[100:101], v[104:105]
	v_pk_fma_f32 v[102:103], v[224:225], s[18:19], v[102:103] op_sel_hi:[1,0,1]
	v_pk_fma_f32 v[100:101], v[222:223], s[18:19], v[100:101] op_sel_hi:[1,0,1]
	global_store_dwordx4 v[200:201], v[100:103], off offset:512
	global_load_dwordx4 v[100:103], v[198:199], off offset:576
	v_cndmask_b32_e64 v104, v187, 4, s[10:11]
	v_mul_hi_i32_i24_e32 v105, 0x6000, v104
	v_mul_i32_i24_e32 v104, 0x6000, v104
	v_lshl_add_u64 v[104:105], s[12:13], 0, v[104:105]
	v_lshl_add_u64 v[198:199], v[104:105], 0, v[142:143]
	v_cndmask_b32_e64 v105, v178, v179, s[10:11]
	v_cndmask_b32_e64 v104, v180, v181, s[10:11]
	s_waitcnt vmcnt(0)
	v_pk_mul_f32 v[98:99], v[98:99], v[102:103]
	v_pk_mul_f32 v[96:97], v[96:97], v[100:101]
	v_pk_fma_f32 v[98:99], v[228:229], s[18:19], v[98:99] op_sel_hi:[1,0,1]
	v_pk_fma_f32 v[96:97], v[226:227], s[18:19], v[96:97] op_sel_hi:[1,0,1]
	global_store_dwordx4 v[200:201], v[96:99], off offset:576
	global_load_dwordx4 v[96:99], v[198:199], off
	v_or_b32_e32 v100, 48, v182
	v_mul_hi_i32 v101, v100, s38
	v_lshrrev_b32_e32 v102, 31, v101
	v_ashrrev_i32_e32 v101, 11, v101
	v_add_u32_e32 v187, v101, v102
	v_mad_i32_i24 v100, v187, s39, v100
	v_lshl_add_u32 v101, v187, 13, v177
	v_lshlrev_b32_e32 v102, 8, v187
	v_cmp_gt_i32_e32 vcc, s85, v100
	s_waitcnt vmcnt(0)
	v_pk_mul_f32 v[94:95], v[94:95], v[98:99]
	v_cndmask_b32_e32 v101, v101, v102, vcc
	v_add_u32_e32 v100, v101, v100
	v_ashrrev_i32_e32 v101, 31, v100
	v_cndmask_b32_e32 v103, v183, v184, vcc
	v_cndmask_b32_e32 v102, v185, v186, vcc
	v_lshlrev_b64 v[200:201], 12, v[100:101]
	v_lshl_add_u64 v[100:101], v[102:103], 0, v[200:201]
	v_lshl_add_u64 v[102:103], v[104:105], 0, v[192:193]
	v_pk_mul_f32 v[92:93], v[92:93], v[96:97]
	v_lshl_add_u64 v[112:113], v[100:101], 0, v[142:143]
	v_lshl_add_u64 v[192:193], v[102:103], 0, v[142:143]
	v_pk_fma_f32 v[94:95], v[118:119], s[18:19], v[94:95] op_sel_hi:[1,0,1]
	v_pk_fma_f32 v[92:93], v[116:117], s[18:19], v[92:93] op_sel_hi:[1,0,1]
	global_load_dwordx4 v[100:103], v[112:113], off
	global_load_dwordx4 v[104:107], v[112:113], off offset:64
	global_load_dwordx4 v[108:111], v[112:113], off offset:512
	s_nop 0
	global_load_dwordx4 v[112:115], v[112:113], off offset:576
	s_nop 0
	global_store_dwordx4 v[192:193], v[92:95], off
	global_load_dwordx4 v[92:95], v[198:199], off offset:64
	s_waitcnt vmcnt(0)
	v_pk_mul_f32 v[90:91], v[90:91], v[94:95]
	v_pk_mul_f32 v[88:89], v[88:89], v[92:93]
	v_pk_fma_f32 v[90:91], v[122:123], s[18:19], v[90:91] op_sel_hi:[1,0,1]
	v_pk_fma_f32 v[88:89], v[120:121], s[18:19], v[88:89] op_sel_hi:[1,0,1]
	global_store_dwordx4 v[192:193], v[88:91], off offset:64
	global_load_dwordx4 v[88:91], v[198:199], off offset:512
	s_waitcnt vmcnt(0)
	v_pk_mul_f32 v[86:87], v[86:87], v[90:91]
	v_pk_mul_f32 v[84:85], v[84:85], v[88:89]
	v_pk_fma_f32 v[86:87], v[126:127], s[18:19], v[86:87] op_sel_hi:[1,0,1]
	v_pk_fma_f32 v[84:85], v[124:125], s[18:19], v[84:85] op_sel_hi:[1,0,1]
	global_store_dwordx4 v[192:193], v[84:87], off offset:512
	global_load_dwordx4 v[84:87], v[198:199], off offset:576
	v_cndmask_b32_e64 v88, v187, 4, vcc
	v_mul_hi_i32_i24_e32 v89, 0x6000, v88
	v_mul_i32_i24_e32 v88, 0x6000, v88
	v_lshl_add_u64 v[88:89], s[12:13], 0, v[88:89]
	v_lshl_add_u64 v[116:117], v[88:89], 0, v[142:143]
	v_cndmask_b32_e32 v89, v178, v179, vcc
	v_cndmask_b32_e32 v88, v180, v181, vcc
	s_waitcnt vmcnt(0)
	v_pk_mul_f32 v[82:83], v[82:83], v[86:87]
	v_pk_mul_f32 v[80:81], v[80:81], v[84:85]
	v_pk_fma_f32 v[82:83], v[190:191], s[18:19], v[82:83] op_sel_hi:[1,0,1]
	v_pk_fma_f32 v[80:81], v[188:189], s[18:19], v[80:81] op_sel_hi:[1,0,1]
	global_store_dwordx4 v[192:193], v[80:83], off offset:576
	global_load_dwordx4 v[80:83], v[116:117], off
	global_load_dwordx4 v[234:237], v[116:117], off offset:64
	global_load_dwordx4 v[238:241], v[116:117], off offset:512
	global_load_dwordx4 v[242:245], v[116:117], off offset:576
	v_add_u32_e32 v84, 0x80, v182
	v_mul_hi_i32 v85, v84, s38
	v_lshrrev_b32_e32 v86, 31, v85
	v_ashrrev_i32_e32 v85, 11, v85
	v_add_u32_e32 v122, v85, v86
	v_mad_i32_i24 v84, v122, s39, v84
	v_lshl_add_u32 v85, v122, 13, v177
	v_lshlrev_b32_e32 v86, 8, v122
	v_cmp_gt_i32_e64 s[10:11], s85, v84
	s_waitcnt vmcnt(0)
	v_pk_mul_f32 v[78:79], v[78:79], v[82:83]
	v_cndmask_b32_e64 v85, v85, v86, s[10:11]
	v_add_u32_e32 v84, v85, v84
	v_ashrrev_i32_e32 v85, 31, v84
	v_cndmask_b32_e64 v87, v183, v184, s[10:11]
	v_cndmask_b32_e64 v86, v185, v186, s[10:11]
	v_lshlrev_b64 v[118:119], 12, v[84:85]
	v_lshl_add_u64 v[84:85], v[86:87], 0, v[118:119]
	v_lshl_add_u64 v[86:87], v[88:89], 0, v[200:201]
	v_pk_mul_f32 v[76:77], v[76:77], v[80:81]
	v_lshl_add_u64 v[96:97], v[84:85], 0, v[142:143]
	v_lshl_add_u64 v[120:121], v[86:87], 0, v[142:143]
	v_pk_fma_f32 v[78:79], v[102:103], s[18:19], v[78:79] op_sel_hi:[1,0,1]
	v_pk_fma_f32 v[76:77], v[100:101], s[18:19], v[76:77] op_sel_hi:[1,0,1]
	global_load_dwordx4 v[84:87], v[96:97], off
	global_load_dwordx4 v[88:91], v[96:97], off offset:64
	global_load_dwordx4 v[92:95], v[96:97], off offset:512
	s_nop 0
	global_load_dwordx4 v[96:99], v[96:97], off offset:576
	s_nop 0
	global_store_dwordx4 v[120:121], v[76:79], off
	v_pk_mul_f32 v[74:75], v[74:75], v[236:237]
	v_pk_mul_f32 v[72:73], v[72:73], v[234:235]
	v_pk_fma_f32 v[74:75], v[106:107], s[18:19], v[74:75] op_sel_hi:[1,0,1]
	v_pk_fma_f32 v[72:73], v[104:105], s[18:19], v[72:73] op_sel_hi:[1,0,1]
	global_store_dwordx4 v[120:121], v[72:75], off offset:64
	v_pk_mul_f32 v[70:71], v[70:71], v[240:241]
	v_pk_mul_f32 v[68:69], v[68:69], v[238:239]
	v_pk_fma_f32 v[70:71], v[110:111], s[18:19], v[70:71] op_sel_hi:[1,0,1]
	v_pk_fma_f32 v[68:69], v[108:109], s[18:19], v[68:69] op_sel_hi:[1,0,1]
	global_store_dwordx4 v[120:121], v[68:71], off offset:512
	v_cndmask_b32_e64 v72, v122, 4, s[10:11]
	v_mul_hi_i32_i24_e32 v73, 0x6000, v72
	v_mul_i32_i24_e32 v72, 0x6000, v72
	v_lshl_add_u64 v[72:73], s[12:13], 0, v[72:73]
	v_lshl_add_u64 v[100:101], v[72:73], 0, v[142:143]
	v_cndmask_b32_e64 v73, v178, v179, s[10:11]
	v_cndmask_b32_e64 v72, v180, v181, s[10:11]
	v_pk_mul_f32 v[66:67], v[66:67], v[244:245]
	v_pk_mul_f32 v[64:65], v[64:65], v[242:243]
	v_pk_fma_f32 v[66:67], v[114:115], s[18:19], v[66:67] op_sel_hi:[1,0,1]
	v_pk_fma_f32 v[64:65], v[112:113], s[18:19], v[64:65] op_sel_hi:[1,0,1]
	global_store_dwordx4 v[120:121], v[64:67], off offset:576
	global_load_dwordx4 v[64:67], v[100:101], off
	global_load_dwordx4 v[234:237], v[100:101], off offset:64
	global_load_dwordx4 v[238:241], v[100:101], off offset:512
	global_load_dwordx4 v[242:245], v[100:101], off offset:576
	v_add_u32_e32 v68, 0x90, v182
	v_mul_hi_i32 v69, v68, s38
	v_lshrrev_b32_e32 v70, 31, v69
	v_ashrrev_i32_e32 v69, 11, v69
	v_add_u32_e32 v106, v69, v70
	v_mad_i32_i24 v68, v106, s39, v68
	v_lshl_add_u32 v69, v106, 13, v177
	v_lshlrev_b32_e32 v70, 8, v106
	v_cmp_gt_i32_e32 vcc, s85, v68
	s_waitcnt vmcnt(0)
	v_pk_mul_f32 v[62:63], v[62:63], v[66:67]
	v_cndmask_b32_e32 v69, v69, v70, vcc
	v_add_u32_e32 v68, v69, v68
	v_ashrrev_i32_e32 v69, 31, v68
	v_cndmask_b32_e32 v71, v183, v184, vcc
	v_cndmask_b32_e32 v70, v185, v186, vcc
	v_lshlrev_b64 v[102:103], 12, v[68:69]
	v_lshl_add_u64 v[68:69], v[70:71], 0, v[102:103]
	v_lshl_add_u64 v[70:71], v[72:73], 0, v[118:119]
	v_pk_mul_f32 v[60:61], v[60:61], v[64:65]
	v_lshl_add_u64 v[80:81], v[68:69], 0, v[142:143]
	v_lshl_add_u64 v[104:105], v[70:71], 0, v[142:143]
	v_pk_fma_f32 v[62:63], v[86:87], s[18:19], v[62:63] op_sel_hi:[1,0,1]
	v_pk_fma_f32 v[60:61], v[84:85], s[18:19], v[60:61] op_sel_hi:[1,0,1]
	global_load_dwordx4 v[68:71], v[80:81], off
	global_load_dwordx4 v[72:75], v[80:81], off offset:64
	global_load_dwordx4 v[76:79], v[80:81], off offset:512
	s_nop 0
	global_load_dwordx4 v[80:83], v[80:81], off offset:576
	s_nop 0
	global_store_dwordx4 v[104:105], v[60:63], off
	v_pk_mul_f32 v[58:59], v[58:59], v[236:237]
	v_pk_mul_f32 v[56:57], v[56:57], v[234:235]
	v_pk_fma_f32 v[58:59], v[90:91], s[18:19], v[58:59] op_sel_hi:[1,0,1]
	v_pk_fma_f32 v[56:57], v[88:89], s[18:19], v[56:57] op_sel_hi:[1,0,1]
	global_store_dwordx4 v[104:105], v[56:59], off offset:64
	v_pk_mul_f32 v[54:55], v[54:55], v[240:241]
	v_pk_mul_f32 v[52:53], v[52:53], v[238:239]
	v_pk_fma_f32 v[54:55], v[94:95], s[18:19], v[54:55] op_sel_hi:[1,0,1]
	v_pk_fma_f32 v[52:53], v[92:93], s[18:19], v[52:53] op_sel_hi:[1,0,1]
	global_store_dwordx4 v[104:105], v[52:55], off offset:512
	v_cndmask_b32_e64 v56, v106, 4, vcc
	v_mul_hi_i32_i24_e32 v57, 0x6000, v56
	v_mul_i32_i24_e32 v56, 0x6000, v56
	v_lshl_add_u64 v[56:57], s[12:13], 0, v[56:57]
	v_lshl_add_u64 v[84:85], v[56:57], 0, v[142:143]
	v_cndmask_b32_e32 v57, v178, v179, vcc
	v_cndmask_b32_e32 v56, v180, v181, vcc
	v_pk_mul_f32 v[50:51], v[50:51], v[244:245]
	v_pk_mul_f32 v[48:49], v[48:49], v[242:243]
	v_pk_fma_f32 v[50:51], v[98:99], s[18:19], v[50:51] op_sel_hi:[1,0,1]
	v_pk_fma_f32 v[48:49], v[96:97], s[18:19], v[48:49] op_sel_hi:[1,0,1]
	global_store_dwordx4 v[104:105], v[48:51], off offset:576
	global_load_dwordx4 v[48:51], v[84:85], off
	global_load_dwordx4 v[234:237], v[84:85], off offset:64
	global_load_dwordx4 v[238:241], v[84:85], off offset:512
	global_load_dwordx4 v[242:245], v[84:85], off offset:576
	v_add_u32_e32 v52, 0xa0, v182
	v_mul_hi_i32 v53, v52, s38
	v_lshrrev_b32_e32 v54, 31, v53
	v_ashrrev_i32_e32 v53, 11, v53
	v_add_u32_e32 v90, v53, v54
	v_mad_i32_i24 v52, v90, s39, v52
	v_lshl_add_u32 v53, v90, 13, v177
	v_lshlrev_b32_e32 v54, 8, v90
	v_cmp_gt_i32_e64 s[10:11], s85, v52
	s_waitcnt vmcnt(0)
	v_pk_mul_f32 v[46:47], v[46:47], v[50:51]
	v_cndmask_b32_e64 v53, v53, v54, s[10:11]
	v_add_u32_e32 v52, v53, v52
	v_ashrrev_i32_e32 v53, 31, v52
	v_cndmask_b32_e64 v55, v183, v184, s[10:11]
	v_cndmask_b32_e64 v54, v185, v186, s[10:11]
	v_lshlrev_b64 v[86:87], 12, v[52:53]
	v_lshl_add_u64 v[52:53], v[54:55], 0, v[86:87]
	v_lshl_add_u64 v[54:55], v[56:57], 0, v[102:103]
	v_pk_mul_f32 v[44:45], v[44:45], v[48:49]
	v_lshl_add_u64 v[64:65], v[52:53], 0, v[142:143]
	v_lshl_add_u64 v[88:89], v[54:55], 0, v[142:143]
	v_pk_fma_f32 v[46:47], v[70:71], s[18:19], v[46:47] op_sel_hi:[1,0,1]
	v_pk_fma_f32 v[44:45], v[68:69], s[18:19], v[44:45] op_sel_hi:[1,0,1]
	global_load_dwordx4 v[52:55], v[64:65], off
	global_load_dwordx4 v[56:59], v[64:65], off offset:64
	global_load_dwordx4 v[60:63], v[64:65], off offset:512
	s_nop 0
	global_load_dwordx4 v[64:67], v[64:65], off offset:576
	s_nop 0
	global_store_dwordx4 v[88:89], v[44:47], off
	v_pk_mul_f32 v[42:43], v[42:43], v[236:237]
	v_pk_mul_f32 v[40:41], v[40:41], v[234:235]
	v_pk_fma_f32 v[42:43], v[74:75], s[18:19], v[42:43] op_sel_hi:[1,0,1]
	v_pk_fma_f32 v[40:41], v[72:73], s[18:19], v[40:41] op_sel_hi:[1,0,1]
	global_store_dwordx4 v[88:89], v[40:43], off offset:64
	v_pk_mul_f32 v[38:39], v[38:39], v[240:241]
	v_pk_mul_f32 v[36:37], v[36:37], v[238:239]
	v_pk_fma_f32 v[38:39], v[78:79], s[18:19], v[38:39] op_sel_hi:[1,0,1]
	v_pk_fma_f32 v[36:37], v[76:77], s[18:19], v[36:37] op_sel_hi:[1,0,1]
	global_store_dwordx4 v[88:89], v[36:39], off offset:512
	v_cndmask_b32_e64 v40, v90, 4, s[10:11]
	v_mul_hi_i32_i24_e32 v41, 0x6000, v40
	v_mul_i32_i24_e32 v40, 0x6000, v40
	v_lshl_add_u64 v[40:41], s[12:13], 0, v[40:41]
	v_lshl_add_u64 v[68:69], v[40:41], 0, v[142:143]
	v_cndmask_b32_e64 v41, v178, v179, s[10:11]
	v_cndmask_b32_e64 v40, v180, v181, s[10:11]
	v_pk_mul_f32 v[34:35], v[34:35], v[244:245]
	v_pk_mul_f32 v[32:33], v[32:33], v[242:243]
	v_pk_fma_f32 v[34:35], v[82:83], s[18:19], v[34:35] op_sel_hi:[1,0,1]
	v_pk_fma_f32 v[32:33], v[80:81], s[18:19], v[32:33] op_sel_hi:[1,0,1]
	global_store_dwordx4 v[88:89], v[32:35], off offset:576
	global_load_dwordx4 v[32:35], v[68:69], off
	global_load_dwordx4 v[234:237], v[68:69], off offset:64
	global_load_dwordx4 v[238:241], v[68:69], off offset:512
	global_load_dwordx4 v[242:245], v[68:69], off offset:576
	v_add_u32_e32 v36, 0xb0, v182
	v_mul_hi_i32 v37, v36, s38
	v_lshrrev_b32_e32 v38, 31, v37
	v_ashrrev_i32_e32 v37, 11, v37
	v_add_u32_e32 v74, v37, v38
	v_mad_i32_i24 v36, v74, s39, v36
	v_lshl_add_u32 v37, v74, 13, v177
	v_lshlrev_b32_e32 v38, 8, v74
	v_cmp_gt_i32_e32 vcc, s85, v36
	s_waitcnt vmcnt(0)
	v_pk_mul_f32 v[30:31], v[30:31], v[34:35]
	v_cndmask_b32_e32 v37, v37, v38, vcc
	v_add_u32_e32 v36, v37, v36
	v_ashrrev_i32_e32 v37, 31, v36
	v_cndmask_b32_e32 v39, v183, v184, vcc
	v_cndmask_b32_e32 v38, v185, v186, vcc
	v_lshlrev_b64 v[70:71], 12, v[36:37]
	v_lshl_add_u64 v[36:37], v[38:39], 0, v[70:71]
	v_lshl_add_u64 v[38:39], v[40:41], 0, v[86:87]
	v_pk_mul_f32 v[28:29], v[28:29], v[32:33]
	v_lshl_add_u64 v[48:49], v[36:37], 0, v[142:143]
	v_lshl_add_u64 v[72:73], v[38:39], 0, v[142:143]
	v_pk_fma_f32 v[30:31], v[54:55], s[18:19], v[30:31] op_sel_hi:[1,0,1]
	v_pk_fma_f32 v[28:29], v[52:53], s[18:19], v[28:29] op_sel_hi:[1,0,1]
	global_load_dwordx4 v[36:39], v[48:49], off
	global_load_dwordx4 v[40:43], v[48:49], off offset:64
	global_load_dwordx4 v[44:47], v[48:49], off offset:512
	s_nop 0
	global_load_dwordx4 v[48:51], v[48:49], off offset:576
	s_nop 0
	global_store_dwordx4 v[72:73], v[28:31], off
	v_pk_mul_f32 v[26:27], v[26:27], v[236:237]
	v_pk_mul_f32 v[24:25], v[24:25], v[234:235]
	v_pk_fma_f32 v[26:27], v[58:59], s[18:19], v[26:27] op_sel_hi:[1,0,1]
	v_pk_fma_f32 v[24:25], v[56:57], s[18:19], v[24:25] op_sel_hi:[1,0,1]
	global_store_dwordx4 v[72:73], v[24:27], off offset:64
	v_pk_mul_f32 v[22:23], v[22:23], v[240:241]
	v_pk_mul_f32 v[20:21], v[20:21], v[238:239]
	v_pk_fma_f32 v[22:23], v[62:63], s[18:19], v[22:23] op_sel_hi:[1,0,1]
	v_pk_fma_f32 v[20:21], v[60:61], s[18:19], v[20:21] op_sel_hi:[1,0,1]
	global_store_dwordx4 v[72:73], v[20:23], off offset:512
	v_cndmask_b32_e64 v24, v74, 4, vcc
	v_mul_hi_i32_i24_e32 v25, 0x6000, v24
	v_mul_i32_i24_e32 v24, 0x6000, v24
	v_lshl_add_u64 v[24:25], s[12:13], 0, v[24:25]
	v_lshl_add_u64 v[24:25], v[24:25], 0, v[142:143]
	v_pk_mul_f32 v[14:15], v[14:15], v[244:245]
	v_pk_mul_f32 v[12:13], v[12:13], v[242:243]
	v_pk_fma_f32 v[14:15], v[66:67], s[18:19], v[14:15] op_sel_hi:[1,0,1]
	v_pk_fma_f32 v[12:13], v[64:65], s[18:19], v[12:13] op_sel_hi:[1,0,1]
	global_store_dwordx4 v[72:73], v[12:15], off offset:576
	global_load_dwordx4 v[12:15], v[24:25], off
	global_load_dwordx4 v[234:237], v[24:25], off offset:64
	global_load_dwordx4 v[238:241], v[24:25], off offset:512
	global_load_dwordx4 v[242:245], v[24:25], off offset:576
	v_cndmask_b32_e32 v21, v178, v179, vcc
	v_cndmask_b32_e32 v20, v180, v181, vcc
	v_lshl_add_u64 v[20:21], v[20:21], 0, v[70:71]
	v_lshl_add_u64 v[20:21], v[20:21], 0, v[142:143]
	s_andn2_b64 vcc, exec, s[6:7]
	s_waitcnt vmcnt(0)
	v_pk_mul_f32 v[14:15], v[18:19], v[14:15]
	v_pk_mul_f32 v[12:13], v[16:17], v[12:13]
	v_pk_fma_f32 v[14:15], v[38:39], s[18:19], v[14:15] op_sel_hi:[1,0,1]
	v_pk_fma_f32 v[12:13], v[36:37], s[18:19], v[12:13] op_sel_hi:[1,0,1]
	global_store_dwordx4 v[20:21], v[12:15], off
	v_pk_mul_f32 v[10:11], v[10:11], v[236:237]
	v_pk_mul_f32 v[8:9], v[8:9], v[234:235]
	v_pk_fma_f32 v[10:11], v[42:43], s[18:19], v[10:11] op_sel_hi:[1,0,1]
	v_pk_fma_f32 v[8:9], v[40:41], s[18:19], v[8:9] op_sel_hi:[1,0,1]
	global_store_dwordx4 v[20:21], v[8:11], off offset:64
	v_pk_mul_f32 v[6:7], v[6:7], v[240:241]
	v_pk_mul_f32 v[4:5], v[4:5], v[238:239]
	v_pk_fma_f32 v[6:7], v[46:47], s[18:19], v[6:7] op_sel_hi:[1,0,1]
	v_pk_fma_f32 v[4:5], v[44:45], s[18:19], v[4:5] op_sel_hi:[1,0,1]
	global_store_dwordx4 v[20:21], v[4:7], off offset:512
	v_pk_mul_f32 v[2:3], v[2:3], v[244:245]
	v_pk_mul_f32 v[0:1], v[0:1], v[242:243]
	v_pk_fma_f32 v[2:3], v[50:51], s[18:19], v[2:3] op_sel_hi:[1,0,1]
	v_pk_fma_f32 v[0:1], v[48:49], s[18:19], v[0:1] op_sel_hi:[1,0,1]
	global_store_dwordx4 v[20:21], v[0:3], off offset:576
	s_cbranch_vccnz .LBB0_848
	s_andn2_b64 vcc, exec, s[8:9]
	s_cbranch_vccnz .LBB0_847
	s_barrier
	s_branch .LBB0_847
